# w_gate_up f32->bf16 conversion moved from bandwidth-bound phase 0 into the idle shadow of the non-scan workgroups in phase 3 (hand-written loop); pool GEMM epilogue scale loads hoisted
# speedup vs baseline: 1.0272x; 1.0166x over previous
; #define LAS __attribute__((address_space(3)))
; __device__ __forceinline__ void convert_items(const Params& p, LAS float* scr, int lane, int gw, int NGW, int it_lo, int it_hi) {
;     unsigned char* ws = p.ws;
;     for (int it = it_lo + gw; it < it_hi; it += NGW) {
;         int r = it;
;         if (r < CV_WIN) { const int kb = r / 417, nb = r % 417, ns = nb * 32; const int nd = ns < 9216 ? ns : (ns < 9248 ? 13312 + (ns - 9216) : ns - 32);
;             transpose_item(p.in[8], IN_COLS, 2048, (bf16_t*)(ws + WS_WIN), kb * 64, ns, nd, scr, lane); continue; } r -= CV_WIN;
; __device__ __forceinline__ void phase0(const Params& p, LAS unsigned char* lds, int wave_s) {
;     const int tid = opaque_tid(wave_s), lane = tid & 63, wave = tid >> 6;
;     const int gw = blockIdx.x * 8 + wave, NGW = gridDim.x * 8;
;     LAS float* scr = (LAS float*)(lds + wave * 8448);
;     unsigned char* ws = p.ws;
;     convert_items(p, scr, lane, gw, NGW, 0, CV_SPLIT);
.LBB0_17:
	s_or_b64 exec, exec, s[0:1]
	s_andn2_b32 s24, s24, 63
	s_cmp_lt_i32 s18, 1
	s_cselect_b64 s[0:1], -1, 0
	s_cmp_gt_i32 s19, 0
	s_cselect_b64 s[4:5], -1, 0
	s_and_b64 s[0:1], s[0:1], s[4:5]
	s_andn2_b64 vcc, exec, s[0:1]
	s_waitcnt lgkmcnt(0)
	s_barrier
	s_cbranch_vccnz .LBB0_70
	s_mov_b32 s3, 0
	s_lshl_b32 s4, s33, 3
	v_mbcnt_lo_u32_b32 v0, -1, s3
	v_mbcnt_hi_u32_b32 v0, -1, v0
	v_or_b32_e32 v13, s24, v0
	s_movk_i32 s3, 0x48a0
	v_ashrrev_i32_e32 v28, 6, v13
	v_and_b32_e32 v16, 63, v13
	v_lshl_add_u32 v12, s2, 3, v28
	v_cmp_gt_i32_e32 vcc, s3, v12
	v_lshlrev_b32_e32 v14, 3, v16
	s_and_saveexec_b64 s[6:7], vcc
	s_cbranch_execz .LBB0_45
	s_movk_i32 s3, 0x2100
	v_mul_lo_u32 v0, v28, s3
	v_lshrrev_b32_e32 v15, 5, v16
	v_and_b32_e32 v30, 31, v13
	v_add_u32_e32 v0, 0, v0
	v_lshlrev_b32_e32 v26, 2, v30
	v_mul_u32_u24_e32 v2, 0x84, v15
	v_lshrrev_b32_e32 v34, 3, v16
	v_and_b32_e32 v32, 56, v14
	v_add3_u32 v17, v0, v26, v2
	v_mul_u32_u24_e32 v2, 0x84, v32
	v_lshlrev_b32_e32 v3, 2, v34
	v_mov_b32_e32 v1, 0
	v_add3_u32 v35, v0, v2, v3
	v_lshlrev_b32_e32 v0, 1, v32
	v_lshl_add_u64 v[10:11], s[22:23], 0, v[0:1]
	s_mov_b64 s[8:9], 0x1480000
	v_lshl_add_u64 v[2:3], v[10:11], 0, s[8:9]
	s_mov_b64 s[8:9], 0xc80000
	v_lshl_add_u64 v[4:5], v[10:11], 0, s[8:9]
	s_mov_b64 s[8:9], 0x480000
	v_lshlrev_b32_e32 v0, 5, v28
	v_lshl_add_u64 v[6:7], v[10:11], 0, s[8:9]
	s_mov_b64 s[8:9], 0x80000
	v_readlane_b32 s36, v254, 0
	v_lshl_add_u32 v39, s2, 8, v0
	v_lshlrev_b32_e32 v0, 11, v28
	v_lshl_add_u64 v[8:9], v[10:11], 0, s[8:9]
	s_mov_b64 s[8:9], 0x64aa000
	v_mov_b32_e32 v27, v1
	v_readlane_b32 s37, v254, 1
	v_readlane_b32 s38, v254, 2
	v_readlane_b32 s39, v254, 3
	v_readlane_b32 s40, v254, 4
	v_readlane_b32 s41, v254, 5
	v_readlane_b32 s42, v254, 6
	v_readlane_b32 s43, v254, 7
	v_readlane_b32 s44, v254, 8
	v_readlane_b32 s45, v254, 9
	v_readlane_b32 s46, v254, 10
	v_readlane_b32 s47, v254, 11
	v_readlane_b32 s48, v254, 12
	v_lshl_add_u32 v40, s2, 14, v0
	v_lshlrev_b32_e32 v0, 3, v28
	v_or_b32_e32 v36, 8, v34
	v_or_b32_e32 v37, 16, v34
	v_or_b32_e32 v38, 24, v34
	v_lshl_add_u64 v[10:11], v[10:11], 0, s[8:9]
	v_lshl_add_u64 v[18:19], s[42:43], 0, v[26:27]
	v_lshl_add_u64 v[20:21], s[38:39], 0, v[26:27]
	v_lshl_add_u64 v[22:23], s[36:37], 0, v[26:27]
	v_lshl_add_u64 v[24:25], s[82:83], 0, v[26:27]
	v_lshl_add_u64 v[26:27], s[68:69], 0, v[26:27]
	s_lshl_b32 s3, s4, 5
	s_lshl_b32 s5, s4, 11
	v_lshl_add_u32 v41, s2, 6, v0
	s_lshl_b32 s25, s4, 3
	s_mov_b64 s[8:9], 0
	v_lshlrev_b32_e32 v28, 2, v30
	s_movk_i32 s30, 0x3000
	s_movk_i32 s31, 0x4000
	s_movk_i32 s34, 0x5000
	s_movk_i32 s35, 0x6000
	s_movk_i32 s36, 0x7000
	s_mov_b32 s37, 0x8000
	s_mov_b32 s38, 0x9000
	s_mov_b32 s39, 0xa000
	s_mov_b32 s40, 0xb000
	s_mov_b32 s41, 0xc000
	s_mov_b32 s42, 0xd000
	s_mov_b32 s43, 0xe000
	s_mov_b32 s44, 0xf000
	v_lshlrev_b32_e32 v30, 1, v32
	s_mov_b32 s45, 0x274a4871
	s_movk_i32 s46, 0x120
	s_mov_b32 s47, 0xd080
	s_movk_i32 s48, 0x489f
	v_mov_b32_e32 v42, 6
	v_add_u32_e32 v43, 0x400, v17
	v_add_u32_e32 v44, 0x800, v17
	v_mov_b32_e32 v45, 0x3400
	v_mov_b32_e32 v46, v12
	v_readlane_b32 s49, v254, 13
	v_readlane_b32 s50, v254, 14
	v_readlane_b32 s51, v254, 15
	s_branch .LBB0_21

; #define EPI_FENCE asm volatile("" ::: "memory")
; __device__ __forceinline__ u32x4 pack8(f32x4 v0, f32x4 v1) { u32x4 w; w.x = pk2(v0[0], v0[1]); w.y = pk2(v0[2], v0[3]); w.z = pk2(v1[0], v1[1]); w.w = pk2(v1[2], v1[3]); return w; }
;     __device__ __forceinline__ void operator()(EPI_ARGS) const {
;         const int col0 = EPI_COL0;
; #pragma unroll
;         for (int ai = 0; ai < 2; ++ai)
; #pragma unroll
;             for (int m = 0; m < 4; ++m) { const int r = EPI_ROW(ai, m); bf16_t* rowp = o + (size_t)r * 1024 + col0;
; #pragma unroll
;                 for (int bj = 0; bj < 2; ++bj) { const f32x4 sc0 = *(const f32x4*)(scale + col0 + bj * 128), sc1 = *(const f32x4*)(scale + col0 + bj * 128 + 4);
;                     *(u32x4*)(rowp + bj * 128) = pack8(acc[ai][bj][m][0] * sc0, acc[ai][bj][m][1] * sc1); }
;                 EPI_FENCE; }
;     }
.LBB0_853:
	v_lshl_or_b32 v142, s63, 8, v148
	v_ashrrev_i32_e32 v143, 31, v142
	v_lshl_add_u64 v[140:141], v[142:143], 2, s[72:73]
	global_load_dwordx4 v[162:165], v[140:141], off
	global_load_dwordx4 v[166:169], v[140:141], off offset:16
	global_load_dwordx4 v[170:173], v[140:141], off offset:512
	global_load_dwordx4 v[174:177], v[140:141], off offset:528
	s_waitcnt vmcnt(0)
	s_nop 1
	v_mov_b64_e32 v[152:153], v[162:163]
	v_mov_b64_e32 v[154:155], v[164:165]
	s_nop 1
	v_mov_b64_e32 v[156:157], v[166:167]
	v_mov_b64_e32 v[158:159], v[168:169]
	v_lshl_add_u32 v144, s44, 8, v146
	v_ashrrev_i32_e32 v145, 31, v144
	v_lshlrev_b64 v[160:161], 11, v[144:145]
	v_lshlrev_b64 v[142:143], 1, v[142:143]
	v_lshl_add_u64 v[160:161], s[8:9], 0, v[160:161]
	v_lshl_add_u64 v[160:161], v[160:161], 0, v[142:143]
	s_andn2_b64 vcc, exec, s[0:1]
	s_mov_b64 s[0:1], -1
	s_nop 0
	v_pk_mul_f32 v[126:127], v[126:127], v[154:155]
	v_pk_mul_f32 v[124:125], v[124:125], v[152:153]
	v_pk_mul_f32 v[152:153], v[122:123], v[158:159]
	v_pk_mul_f32 v[122:123], v[120:121], v[156:157]
	v_cvt_pk_bf16_f32 v120, v124, v125
	v_cvt_pk_bf16_f32 v121, v126, v127
	v_cvt_pk_bf16_f32 v122, v122, v123
	v_cvt_pk_bf16_f32 v123, v152, v153
	global_store_dwordx4 v[160:161], v[120:123], off
	s_nop 1
	v_mov_b64_e32 v[120:121], v[170:171]
	v_mov_b64_e32 v[122:123], v[172:173]
	s_nop 0
	s_nop 1
	v_mov_b64_e32 v[124:125], v[174:175]
	v_mov_b64_e32 v[126:127], v[176:177]
	s_nop 0
	v_pk_mul_f32 v[118:119], v[118:119], v[122:123]
	v_pk_mul_f32 v[116:117], v[116:117], v[120:121]
	s_nop 0
	v_pk_mul_f32 v[120:121], v[114:115], v[126:127]
	v_pk_mul_f32 v[114:115], v[112:113], v[124:125]
	v_cvt_pk_bf16_f32 v112, v116, v117
	v_cvt_pk_bf16_f32 v113, v118, v119
	v_cvt_pk_bf16_f32 v114, v114, v115
	v_cvt_pk_bf16_f32 v115, v120, v121
	global_store_dwordx4 v[160:161], v[112:115], off offset:256
	s_nop 1
	v_mov_b64_e32 v[112:113], v[162:163]
	v_mov_b64_e32 v[114:115], v[164:165]
	s_nop 1
	v_mov_b64_e32 v[116:117], v[166:167]
	v_mov_b64_e32 v[118:119], v[168:169]
	v_or_b32_e32 v120, 16, v144
	v_ashrrev_i32_e32 v121, 31, v120
	v_lshlrev_b64 v[120:121], 11, v[120:121]
	v_lshl_add_u64 v[120:121], s[8:9], 0, v[120:121]
	v_lshl_add_u64 v[120:121], v[120:121], 0, v[142:143]
	s_nop 0
	v_pk_mul_f32 v[110:111], v[110:111], v[114:115]
	v_pk_mul_f32 v[108:109], v[108:109], v[112:113]
	s_nop 0
	v_pk_mul_f32 v[112:113], v[106:107], v[118:119]
	v_pk_mul_f32 v[106:107], v[104:105], v[116:117]
	v_cvt_pk_bf16_f32 v104, v108, v109
	v_cvt_pk_bf16_f32 v105, v110, v111
	v_cvt_pk_bf16_f32 v106, v106, v107
	v_cvt_pk_bf16_f32 v107, v112, v113
	global_store_dwordx4 v[120:121], v[104:107], off
	s_nop 1
	v_mov_b64_e32 v[104:105], v[170:171]
	v_mov_b64_e32 v[106:107], v[172:173]
	s_nop 0
	s_nop 1
	v_mov_b64_e32 v[108:109], v[174:175]
	v_mov_b64_e32 v[110:111], v[176:177]
	s_nop 0
	v_pk_mul_f32 v[102:103], v[102:103], v[106:107]
	v_pk_mul_f32 v[100:101], v[100:101], v[104:105]
	s_nop 0
	v_pk_mul_f32 v[104:105], v[98:99], v[110:111]
	v_pk_mul_f32 v[98:99], v[96:97], v[108:109]
	v_cvt_pk_bf16_f32 v96, v100, v101
	v_cvt_pk_bf16_f32 v97, v102, v103
	v_cvt_pk_bf16_f32 v98, v98, v99
	v_cvt_pk_bf16_f32 v99, v104, v105
	global_store_dwordx4 v[120:121], v[96:99], off offset:256
	s_nop 1
	v_mov_b64_e32 v[96:97], v[162:163]
	v_mov_b64_e32 v[98:99], v[164:165]
	s_nop 1
	v_mov_b64_e32 v[100:101], v[166:167]
	v_mov_b64_e32 v[102:103], v[168:169]
	v_or_b32_e32 v104, 32, v144
	v_ashrrev_i32_e32 v105, 31, v104
	v_lshlrev_b64 v[104:105], 11, v[104:105]
	v_lshl_add_u64 v[104:105], s[8:9], 0, v[104:105]
	v_lshl_add_u64 v[104:105], v[104:105], 0, v[142:143]
	s_nop 0
	v_pk_mul_f32 v[94:95], v[94:95], v[98:99]
	v_pk_mul_f32 v[92:93], v[92:93], v[96:97]
	s_nop 0
	v_pk_mul_f32 v[96:97], v[90:91], v[102:103]
	v_pk_mul_f32 v[90:91], v[88:89], v[100:101]
	v_cvt_pk_bf16_f32 v88, v92, v93
	v_cvt_pk_bf16_f32 v89, v94, v95
	v_cvt_pk_bf16_f32 v90, v90, v91
	v_cvt_pk_bf16_f32 v91, v96, v97
	global_store_dwordx4 v[104:105], v[88:91], off
	s_nop 1
	v_mov_b64_e32 v[88:89], v[170:171]
	v_mov_b64_e32 v[90:91], v[172:173]
	s_nop 0
	s_nop 1
	v_mov_b64_e32 v[92:93], v[174:175]
	v_mov_b64_e32 v[94:95], v[176:177]
	s_nop 0
	v_pk_mul_f32 v[86:87], v[86:87], v[90:91]
	v_pk_mul_f32 v[84:85], v[84:85], v[88:89]
	s_nop 0
	v_pk_mul_f32 v[88:89], v[82:83], v[94:95]
	v_pk_mul_f32 v[82:83], v[80:81], v[92:93]
	v_cvt_pk_bf16_f32 v80, v84, v85
	v_cvt_pk_bf16_f32 v81, v86, v87
	v_cvt_pk_bf16_f32 v82, v82, v83
	v_cvt_pk_bf16_f32 v83, v88, v89
	global_store_dwordx4 v[104:105], v[80:83], off offset:256
	s_nop 1
	v_mov_b64_e32 v[80:81], v[162:163]
	v_mov_b64_e32 v[82:83], v[164:165]
	s_nop 1
	v_mov_b64_e32 v[84:85], v[166:167]
	v_mov_b64_e32 v[86:87], v[168:169]
	v_or_b32_e32 v88, 48, v144
	v_ashrrev_i32_e32 v89, 31, v88
	v_lshlrev_b64 v[88:89], 11, v[88:89]
	v_lshl_add_u64 v[88:89], s[8:9], 0, v[88:89]
	v_lshl_add_u64 v[88:89], v[88:89], 0, v[142:143]
	s_nop 0
	v_pk_mul_f32 v[78:79], v[78:79], v[82:83]
	v_pk_mul_f32 v[76:77], v[76:77], v[80:81]
	s_nop 0
	v_pk_mul_f32 v[80:81], v[70:71], v[86:87]
	v_pk_mul_f32 v[70:71], v[68:69], v[84:85]
	v_cvt_pk_bf16_f32 v68, v76, v77
	v_cvt_pk_bf16_f32 v69, v78, v79
	v_cvt_pk_bf16_f32 v70, v70, v71
	v_cvt_pk_bf16_f32 v71, v80, v81
	global_store_dwordx4 v[88:89], v[68:71], off
	s_nop 1
	v_mov_b64_e32 v[68:69], v[170:171]
	v_mov_b64_e32 v[70:71], v[172:173]
	s_nop 0
	s_nop 1
	v_mov_b64_e32 v[76:77], v[174:175]
	v_mov_b64_e32 v[78:79], v[176:177]
	s_nop 0
	v_pk_mul_f32 v[62:63], v[62:63], v[70:71]
; #define EPI_FENCE asm volatile("" ::: "memory")
; __device__ __forceinline__ u32x4 pack8(f32x4 v0, f32x4 v1) { u32x4 w; w.x = pk2(v0[0], v0[1]); w.y = pk2(v0[2], v0[3]); w.z = pk2(v1[0], v1[1]); w.w = pk2(v1[2], v1[3]); return w; }
;     __device__ __forceinline__ void operator()(EPI_ARGS) const {
;         const int col0 = EPI_COL0;
; #pragma unroll
;         for (int ai = 0; ai < 2; ++ai)
; #pragma unroll
;             for (int m = 0; m < 4; ++m) { const int r = EPI_ROW(ai, m); bf16_t* rowp = o + (size_t)r * 1024 + col0;
; #pragma unroll
;                 for (int bj = 0; bj < 2; ++bj) { const f32x4 sc0 = *(const f32x4*)(scale + col0 + bj * 128), sc1 = *(const f32x4*)(scale + col0 + bj * 128 + 4);
;                     *(u32x4*)(rowp + bj * 128) = pack8(acc[ai][bj][m][0] * sc0, acc[ai][bj][m][1] * sc1); }
;                 EPI_FENCE; }
;     }
	v_pk_mul_f32 v[60:61], v[60:61], v[68:69]
	s_nop 0
	v_pk_mul_f32 v[68:69], v[54:55], v[78:79]
	v_pk_mul_f32 v[54:55], v[52:53], v[76:77]
	v_cvt_pk_bf16_f32 v52, v60, v61
	v_cvt_pk_bf16_f32 v53, v62, v63
	v_cvt_pk_bf16_f32 v54, v54, v55
	v_cvt_pk_bf16_f32 v55, v68, v69
	global_store_dwordx4 v[88:89], v[52:55], off offset:256
	s_nop 1
	v_mov_b64_e32 v[52:53], v[162:163]
	v_mov_b64_e32 v[54:55], v[164:165]
	s_nop 1
	v_mov_b64_e32 v[60:61], v[166:167]
	v_mov_b64_e32 v[62:63], v[168:169]
	v_add_u32_e32 v68, 0x80, v144
	v_ashrrev_i32_e32 v69, 31, v68
	v_lshlrev_b64 v[68:69], 11, v[68:69]
	v_lshl_add_u64 v[68:69], s[8:9], 0, v[68:69]
	v_lshl_add_u64 v[68:69], v[68:69], 0, v[142:143]
	s_nop 0
	v_pk_mul_f32 v[54:55], v[74:75], v[54:55]
	v_pk_mul_f32 v[52:53], v[72:73], v[52:53]
	s_nop 0
	v_pk_mul_f32 v[62:63], v[66:67], v[62:63]
	v_pk_mul_f32 v[60:61], v[64:65], v[60:61]
	v_cvt_pk_bf16_f32 v52, v52, v53
	v_cvt_pk_bf16_f32 v53, v54, v55
	v_cvt_pk_bf16_f32 v54, v60, v61
	v_cvt_pk_bf16_f32 v55, v62, v63
	global_store_dwordx4 v[68:69], v[52:55], off
	s_nop 1
	v_mov_b64_e32 v[52:53], v[170:171]
	v_mov_b64_e32 v[54:55], v[172:173]
	s_nop 0
	s_nop 1
	v_mov_b64_e32 v[60:61], v[174:175]
	v_mov_b64_e32 v[62:63], v[176:177]
	s_nop 0
	v_pk_mul_f32 v[54:55], v[58:59], v[54:55]
	v_pk_mul_f32 v[52:53], v[56:57], v[52:53]
	s_nop 0
	v_pk_mul_f32 v[56:57], v[50:51], v[62:63]
	v_pk_mul_f32 v[50:51], v[48:49], v[60:61]
	v_cvt_pk_bf16_f32 v48, v52, v53
	v_cvt_pk_bf16_f32 v49, v54, v55
	v_cvt_pk_bf16_f32 v50, v50, v51
	v_cvt_pk_bf16_f32 v51, v56, v57
	global_store_dwordx4 v[68:69], v[48:51], off offset:256
	s_nop 1
	v_mov_b64_e32 v[48:49], v[162:163]
	v_mov_b64_e32 v[50:51], v[164:165]
	s_nop 1
	v_mov_b64_e32 v[52:53], v[166:167]
	v_mov_b64_e32 v[54:55], v[168:169]
	v_add_u32_e32 v56, 0x90, v144
	v_ashrrev_i32_e32 v57, 31, v56
	v_lshlrev_b64 v[56:57], 11, v[56:57]
	v_lshl_add_u64 v[56:57], s[8:9], 0, v[56:57]
	v_lshl_add_u64 v[56:57], v[56:57], 0, v[142:143]
	s_nop 0
	v_pk_mul_f32 v[46:47], v[46:47], v[50:51]
	v_pk_mul_f32 v[44:45], v[44:45], v[48:49]
	s_nop 0
	v_pk_mul_f32 v[48:49], v[42:43], v[54:55]
	v_pk_mul_f32 v[42:43], v[40:41], v[52:53]
	v_cvt_pk_bf16_f32 v40, v44, v45
	v_cvt_pk_bf16_f32 v41, v46, v47
	v_cvt_pk_bf16_f32 v42, v42, v43
	v_cvt_pk_bf16_f32 v43, v48, v49
	global_store_dwordx4 v[56:57], v[40:43], off
	s_nop 1
	v_mov_b64_e32 v[40:41], v[170:171]
	v_mov_b64_e32 v[42:43], v[172:173]
	s_nop 0
	s_nop 1
	v_mov_b64_e32 v[44:45], v[174:175]
	v_mov_b64_e32 v[46:47], v[176:177]
	s_nop 0
	v_pk_mul_f32 v[38:39], v[38:39], v[42:43]
	v_pk_mul_f32 v[36:37], v[36:37], v[40:41]
	s_nop 0
	v_pk_mul_f32 v[40:41], v[34:35], v[46:47]
	v_pk_mul_f32 v[34:35], v[32:33], v[44:45]
	v_cvt_pk_bf16_f32 v32, v36, v37
	v_cvt_pk_bf16_f32 v33, v38, v39
	v_cvt_pk_bf16_f32 v34, v34, v35
	v_cvt_pk_bf16_f32 v35, v40, v41
	global_store_dwordx4 v[56:57], v[32:35], off offset:256
	s_nop 1
	v_mov_b64_e32 v[32:33], v[162:163]
	v_mov_b64_e32 v[34:35], v[164:165]
	s_nop 1
	v_mov_b64_e32 v[36:37], v[166:167]
	v_mov_b64_e32 v[38:39], v[168:169]
	v_add_u32_e32 v40, 0xa0, v144
	v_ashrrev_i32_e32 v41, 31, v40
	v_lshlrev_b64 v[40:41], 11, v[40:41]
	v_lshl_add_u64 v[40:41], s[8:9], 0, v[40:41]
	v_lshl_add_u64 v[40:41], v[40:41], 0, v[142:143]
	s_nop 0
	v_pk_mul_f32 v[30:31], v[30:31], v[34:35]
	v_pk_mul_f32 v[28:29], v[28:29], v[32:33]
	s_nop 0
	v_pk_mul_f32 v[32:33], v[26:27], v[38:39]
	v_pk_mul_f32 v[26:27], v[24:25], v[36:37]
	v_cvt_pk_bf16_f32 v24, v28, v29
	v_cvt_pk_bf16_f32 v25, v30, v31
	v_cvt_pk_bf16_f32 v26, v26, v27
	v_cvt_pk_bf16_f32 v27, v32, v33
	global_store_dwordx4 v[40:41], v[24:27], off
	s_nop 1
	v_mov_b64_e32 v[24:25], v[170:171]
	v_mov_b64_e32 v[26:27], v[172:173]
	s_nop 0
	s_nop 1
	v_mov_b64_e32 v[28:29], v[174:175]
	v_mov_b64_e32 v[30:31], v[176:177]
	s_nop 0
	v_pk_mul_f32 v[22:23], v[22:23], v[26:27]
	v_pk_mul_f32 v[20:21], v[20:21], v[24:25]
	s_nop 0
	v_pk_mul_f32 v[24:25], v[18:19], v[30:31]
	v_pk_mul_f32 v[18:19], v[16:17], v[28:29]
	v_cvt_pk_bf16_f32 v16, v20, v21
	v_cvt_pk_bf16_f32 v17, v22, v23
	v_cvt_pk_bf16_f32 v18, v18, v19
	v_cvt_pk_bf16_f32 v19, v24, v25
	global_store_dwordx4 v[40:41], v[16:19], off offset:256
	s_nop 1
	v_mov_b64_e32 v[16:17], v[162:163]
	v_mov_b64_e32 v[18:19], v[164:165]
	s_nop 1
	v_mov_b64_e32 v[20:21], v[166:167]
	v_mov_b64_e32 v[22:23], v[168:169]
	v_add_u32_e32 v24, 0xb0, v144
	v_ashrrev_i32_e32 v25, 31, v24
	v_lshlrev_b64 v[24:25], 11, v[24:25]
	v_lshl_add_u64 v[24:25], s[8:9], 0, v[24:25]
	v_lshl_add_u64 v[24:25], v[24:25], 0, v[142:143]
	s_nop 0
	v_pk_mul_f32 v[14:15], v[14:15], v[18:19]
	v_pk_mul_f32 v[12:13], v[12:13], v[16:17]
	s_nop 0
	v_pk_mul_f32 v[16:17], v[10:11], v[22:23]
	v_pk_mul_f32 v[10:11], v[8:9], v[20:21]
	v_cvt_pk_bf16_f32 v8, v12, v13
	v_cvt_pk_bf16_f32 v9, v14, v15
	v_cvt_pk_bf16_f32 v10, v10, v11
	v_cvt_pk_bf16_f32 v11, v16, v17
	global_store_dwordx4 v[24:25], v[8:11], off
	s_nop 1
	v_mov_b64_e32 v[8:9], v[170:171]
	v_mov_b64_e32 v[10:11], v[172:173]
	s_nop 0
	s_nop 1
	v_mov_b64_e32 v[12:13], v[174:175]
	v_mov_b64_e32 v[14:15], v[176:177]
	s_nop 0
	v_pk_mul_f32 v[6:7], v[6:7], v[10:11]
	v_pk_mul_f32 v[4:5], v[4:5], v[8:9]
	s_nop 0
	v_pk_mul_f32 v[8:9], v[2:3], v[14:15]
	v_pk_mul_f32 v[2:3], v[0:1], v[12:13]
	v_cvt_pk_bf16_f32 v0, v4, v5
	v_cvt_pk_bf16_f32 v1, v6, v7
	v_cvt_pk_bf16_f32 v2, v2, v3
	v_cvt_pk_bf16_f32 v3, v8, v9
	global_store_dwordx4 v[24:25], v[0:3], off offset:256
	s_cbranch_vccnz .LBB0_844
	s_andn2_b64 vcc, exec, s[6:7]
	s_cbranch_vccnz .LBB0_843
	s_barrier
	s_branch .LBB0_843

; #define LAS __attribute__((address_space(3)))
; __device__ __forceinline__ unsigned pk2(float lo, float hi) { const f32x2_t v = {lo, hi}; const bf16x2_t b = __builtin_convertvector(v, bf16x2_t); return __builtin_bit_cast(unsigned, b); }
; #define LDS_WAIT() asm volatile("s_waitcnt lgkmcnt(0)" ::: "memory")
; __device__ __forceinline__ void transpose_item(const float* W, int N, int K, bf16_t* WT, int k0, int n0src, int n0dst, LAS float* scr, int lane) {
;     float tv[32];
; #pragma unroll
;     for (int i = 0; i < 32; ++i) tv[i] = __builtin_nontemporal_load(&W[(size_t)(k0 + 2 * i + (lane >> 5)) * N + n0src + (lane & 31)]);
; #pragma unroll
;     for (int i = 0; i < 32; ++i) scr[(2 * i + (lane >> 5)) * 33 + (lane & 31)] = tv[i];
;     LDS_WAIT();
;     const int c = lane & 7;
; #pragma unroll
;     for (int j = 0; j < 4; ++j) { const int n = (lane >> 3) + 8 * j; const LAS float* s = scr + (8 * c) * 33 + n;
;         u32x4 o; o.x = pk2(s[0 * 33], s[1 * 33]); o.y = pk2(s[2 * 33], s[3 * 33]); o.z = pk2(s[4 * 33], s[5 * 33]); o.w = pk2(s[6 * 33], s[7 * 33]);
;         *(u32x4*)(WT + (size_t)(n0dst + n) * K + k0 + 8 * c) = o; }
;     LDS_WAIT();
; }
; __device__ __forceinline__ void convert_items(const Params& p, LAS float* scr, int lane, int gw, int NGW, int it_lo, int it_hi) {
;     ...
;         if (r < CV_GATE) { const int kb = r / 352, nb = r % 352, ns = nb * 32; int nd; if (ns < DFF) nd = 256 * (ns / 128) + (ns % 128); else { const int j = ns - DFF; nd = 256 * (j / 128) + 128 + (j % 128); }
;             transpose_item(p.in[19], 2 * DFF, 2048, (bf16_t*)(ws + WS_WGATE), kb * 64, ns, nd, scr, lane); continue; } r -= CV_GATE;
.LBB0_896:
	s_or_b64 exec, exec, s[0:1]
	s_mov_b64 exec, -1
	v_mbcnt_lo_u32_b32 v0, -1, 0
	v_mbcnt_hi_u32_b32 v0, -1, v0
	s_lshr_b32 s84, s24, 6
	s_sub_i32 s85, s2, 64
	s_lshl_b32 s85, s85, 3
	s_add_i32 s85, s85, s84
	v_readlane_b32 s86, v254, 6
	v_readlane_b32 s87, v254, 7
	s_mul_i32 s90, s84, 0x2100
	v_lshrrev_b32_e32 v1, 5, v0
	v_and_b32_e32 v2, 31, v0
	v_mul_u32_u24_e32 v3, 0xb000, v1
	v_lshl_add_u32 v3, v2, 2, v3
	v_mul_u32_u24_e32 v4, 33, v1
	v_add_u32_e32 v4, v4, v2
	v_lshl_add_u32 v4, v4, 2, s90
	v_and_b32_e32 v5, 7, v0
	v_lshrrev_b32_e32 v6, 3, v0
	v_mul_u32_u24_e32 v7, 0x420, v5
	v_lshl_add_u32 v7, v6, 2, v7
	v_add_u32_e32 v7, s90, v7
	v_lshlrev_b32_e32 v8, 12, v6
	v_lshl_add_u32 v8, v5, 4, v8
	v_add_u32_e32 v9, 0x8000, v8
	v_add_u32_e32 v10, 0x10000, v8
	v_add_u32_e32 v11, 0x18000, v8
.Lgconv_loop:
	s_cmp_lt_u32 s85, 0x2c00
	s_cbranch_scc0 .Lgconv_done
	s_mul_i32 s91, s85, 0xba2f
	s_lshr_b32 s91, s91, 24
	s_mul_i32 s92, s91, 0x160
	s_sub_i32 s92, s85, s92
	s_lshl_b32 s92, s92, 5
	s_cmp_lt_u32 s92, 0x1600
	s_cselect_b32 s93, 0, 0x1600
	s_cselect_b32 s94, 0, 0x80
	s_sub_i32 s93, s92, s93
	s_lshr_b32 s95, s93, 7
	s_lshl_b32 s95, s95, 8
	s_and_b32 s93, s93, 0x7f
	s_add_i32 s95, s95, s93
	s_add_i32 s95, s95, s94
	s_mul_i32 s96, s91, 0x2c0000
	s_lshl_b32 s97, s92, 2
	s_add_i32 s96, s96, s97
	s_add_u32 s96, s86, s96
	s_addc_u32 s97, s87, 0
	global_load_dword v16, v3, s[96:97] nt
	s_add_u32 s96, s96, 0x16000
	s_addc_u32 s97, s97, 0
	global_load_dword v17, v3, s[96:97] nt
	s_add_u32 s96, s96, 0x16000
	s_addc_u32 s97, s97, 0
	global_load_dword v18, v3, s[96:97] nt
	s_add_u32 s96, s96, 0x16000
	s_addc_u32 s97, s97, 0
	global_load_dword v19, v3, s[96:97] nt
	s_add_u32 s96, s96, 0x16000
	s_addc_u32 s97, s97, 0
	global_load_dword v20, v3, s[96:97] nt
	s_add_u32 s96, s96, 0x16000
	s_addc_u32 s97, s97, 0
	global_load_dword v21, v3, s[96:97] nt
	s_add_u32 s96, s96, 0x16000
	s_addc_u32 s97, s97, 0
	global_load_dword v22, v3, s[96:97] nt
	s_add_u32 s96, s96, 0x16000
	s_addc_u32 s97, s97, 0
	global_load_dword v23, v3, s[96:97] nt
	s_add_u32 s96, s96, 0x16000
	s_addc_u32 s97, s97, 0
	global_load_dword v24, v3, s[96:97] nt
	s_add_u32 s96, s96, 0x16000
	s_addc_u32 s97, s97, 0
	global_load_dword v25, v3, s[96:97] nt
	s_add_u32 s96, s96, 0x16000
	s_addc_u32 s97, s97, 0
	global_load_dword v26, v3, s[96:97] nt
	s_add_u32 s96, s96, 0x16000
	s_addc_u32 s97, s97, 0
	global_load_dword v27, v3, s[96:97] nt
	s_add_u32 s96, s96, 0x16000
	s_addc_u32 s97, s97, 0
	global_load_dword v28, v3, s[96:97] nt
	s_add_u32 s96, s96, 0x16000
	s_addc_u32 s97, s97, 0
	global_load_dword v29, v3, s[96:97] nt
	s_add_u32 s96, s96, 0x16000
	s_addc_u32 s97, s97, 0
	global_load_dword v30, v3, s[96:97] nt
	s_add_u32 s96, s96, 0x16000
	s_addc_u32 s97, s97, 0
	global_load_dword v31, v3, s[96:97] nt
	s_add_u32 s96, s96, 0x16000
	s_addc_u32 s97, s97, 0
	global_load_dword v32, v3, s[96:97] nt
	s_add_u32 s96, s96, 0x16000
	s_addc_u32 s97, s97, 0
	global_load_dword v33, v3, s[96:97] nt
	s_add_u32 s96, s96, 0x16000
	s_addc_u32 s97, s97, 0
	global_load_dword v34, v3, s[96:97] nt
	s_add_u32 s96, s96, 0x16000
	s_addc_u32 s97, s97, 0
	global_load_dword v35, v3, s[96:97] nt
	s_add_u32 s96, s96, 0x16000
	s_addc_u32 s97, s97, 0
	global_load_dword v36, v3, s[96:97] nt
	s_add_u32 s96, s96, 0x16000
	s_addc_u32 s97, s97, 0
	global_load_dword v37, v3, s[96:97] nt
	s_add_u32 s96, s96, 0x16000
	s_addc_u32 s97, s97, 0
	global_load_dword v38, v3, s[96:97] nt
	s_add_u32 s96, s96, 0x16000
	s_addc_u32 s97, s97, 0
	global_load_dword v39, v3, s[96:97] nt
	s_add_u32 s96, s96, 0x16000
	s_addc_u32 s97, s97, 0
	global_load_dword v40, v3, s[96:97] nt
	s_add_u32 s96, s96, 0x16000
	s_addc_u32 s97, s97, 0
	global_load_dword v41, v3, s[96:97] nt
	s_add_u32 s96, s96, 0x16000
	s_addc_u32 s97, s97, 0
	global_load_dword v42, v3, s[96:97] nt
	s_add_u32 s96, s96, 0x16000
	s_addc_u32 s97, s97, 0
	global_load_dword v43, v3, s[96:97] nt
	s_add_u32 s96, s96, 0x16000
	s_addc_u32 s97, s97, 0
	global_load_dword v44, v3, s[96:97] nt
	s_add_u32 s96, s96, 0x16000
	s_addc_u32 s97, s97, 0
	global_load_dword v45, v3, s[96:97] nt
	s_add_u32 s96, s96, 0x16000
	s_addc_u32 s97, s97, 0
	global_load_dword v46, v3, s[96:97] nt
	s_add_u32 s96, s96, 0x16000
	s_addc_u32 s97, s97, 0
	global_load_dword v47, v3, s[96:97] nt
	s_lshl_b32 s92, s95, 12
	s_lshl_b32 s93, s91, 7
	s_add_i32 s92, s92, s93
	s_add_u32 s92, s22, s92
	s_addc_u32 s93, s23, 0
	s_add_u32 s92, s92, 0x1480000
	s_addc_u32 s93, s93, 0
	s_waitcnt vmcnt(31)
	ds_write_b32 v4, v16
	s_waitcnt vmcnt(30)
; #define LAS __attribute__((address_space(3)))
; __device__ __forceinline__ unsigned pk2(float lo, float hi) { const f32x2_t v = {lo, hi}; const bf16x2_t b = __builtin_convertvector(v, bf16x2_t); return __builtin_bit_cast(unsigned, b); }
; #define LDS_WAIT() asm volatile("s_waitcnt lgkmcnt(0)" ::: "memory")
; __device__ __forceinline__ void transpose_item(const float* W, int N, int K, bf16_t* WT, int k0, int n0src, int n0dst, LAS float* scr, int lane) {
;     ...
;     for (int i = 0; i < 32; ++i) scr[(2 * i + (lane >> 5)) * 33 + (lane & 31)] = tv[i];
;     LDS_WAIT();
;     const int c = lane & 7;
; #pragma unroll
;     for (int j = 0; j < 4; ++j) { const int n = (lane >> 3) + 8 * j; const LAS float* s = scr + (8 * c) * 33 + n;
;         u32x4 o; o.x = pk2(s[0 * 33], s[1 * 33]); o.y = pk2(s[2 * 33], s[3 * 33]); o.z = pk2(s[4 * 33], s[5 * 33]); o.w = pk2(s[6 * 33], s[7 * 33]);
;         *(u32x4*)(WT + (size_t)(n0dst + n) * K + k0 + 8 * c) = o; }
;     LDS_WAIT();
; }
	ds_write_b32 v4, v17 offset:264
	s_waitcnt vmcnt(29)
	ds_write_b32 v4, v18 offset:528
	s_waitcnt vmcnt(28)
	ds_write_b32 v4, v19 offset:792
	s_waitcnt vmcnt(27)
	ds_write_b32 v4, v20 offset:1056
	s_waitcnt vmcnt(26)
	ds_write_b32 v4, v21 offset:1320
	s_waitcnt vmcnt(25)
	ds_write_b32 v4, v22 offset:1584
	s_waitcnt vmcnt(24)
	ds_write_b32 v4, v23 offset:1848
	s_waitcnt vmcnt(23)
	ds_write_b32 v4, v24 offset:2112
	s_waitcnt vmcnt(22)
	ds_write_b32 v4, v25 offset:2376
	s_waitcnt vmcnt(21)
	ds_write_b32 v4, v26 offset:2640
	s_waitcnt vmcnt(20)
	ds_write_b32 v4, v27 offset:2904
	s_waitcnt vmcnt(19)
	ds_write_b32 v4, v28 offset:3168
	s_waitcnt vmcnt(18)
	ds_write_b32 v4, v29 offset:3432
	s_waitcnt vmcnt(17)
	ds_write_b32 v4, v30 offset:3696
	s_waitcnt vmcnt(16)
	ds_write_b32 v4, v31 offset:3960
	s_waitcnt vmcnt(15)
	ds_write_b32 v4, v32 offset:4224
	s_waitcnt vmcnt(14)
	ds_write_b32 v4, v33 offset:4488
	s_waitcnt vmcnt(13)
	ds_write_b32 v4, v34 offset:4752
	s_waitcnt vmcnt(12)
	ds_write_b32 v4, v35 offset:5016
	s_waitcnt vmcnt(11)
	ds_write_b32 v4, v36 offset:5280
	s_waitcnt vmcnt(10)
	ds_write_b32 v4, v37 offset:5544
	s_waitcnt vmcnt(9)
	ds_write_b32 v4, v38 offset:5808
	s_waitcnt vmcnt(8)
	ds_write_b32 v4, v39 offset:6072
	s_waitcnt vmcnt(7)
	ds_write_b32 v4, v40 offset:6336
	s_waitcnt vmcnt(6)
	ds_write_b32 v4, v41 offset:6600
	s_waitcnt vmcnt(5)
	ds_write_b32 v4, v42 offset:6864
	s_waitcnt vmcnt(4)
	ds_write_b32 v4, v43 offset:7128
	s_waitcnt vmcnt(3)
	ds_write_b32 v4, v44 offset:7392
	s_waitcnt vmcnt(2)
	ds_write_b32 v4, v45 offset:7656
	s_waitcnt vmcnt(1)
	ds_write_b32 v4, v46 offset:7920
	s_waitcnt vmcnt(0)
	ds_write_b32 v4, v47 offset:8184
	s_waitcnt lgkmcnt(0)
	ds_read_b32 v48, v7
	ds_read_b32 v49, v7 offset:132
	ds_read_b32 v50, v7 offset:264
	ds_read_b32 v51, v7 offset:396
	ds_read_b32 v52, v7 offset:528
	ds_read_b32 v53, v7 offset:660
	ds_read_b32 v54, v7 offset:792
	ds_read_b32 v55, v7 offset:924
	s_waitcnt lgkmcnt(0)
	v_cvt_pk_bf16_f32 v80, v48, v49
	v_cvt_pk_bf16_f32 v81, v50, v51
	v_cvt_pk_bf16_f32 v82, v52, v53
	v_cvt_pk_bf16_f32 v83, v54, v55
	global_store_dwordx4 v8, v[80:83], s[92:93]
	ds_read_b32 v56, v7 offset:32
	ds_read_b32 v57, v7 offset:164
	ds_read_b32 v58, v7 offset:296
	ds_read_b32 v59, v7 offset:428
	ds_read_b32 v60, v7 offset:560
	ds_read_b32 v61, v7 offset:692
	ds_read_b32 v62, v7 offset:824
	ds_read_b32 v63, v7 offset:956
	s_waitcnt lgkmcnt(0)
	v_cvt_pk_bf16_f32 v84, v56, v57
	v_cvt_pk_bf16_f32 v85, v58, v59
	v_cvt_pk_bf16_f32 v86, v60, v61
	v_cvt_pk_bf16_f32 v87, v62, v63
	global_store_dwordx4 v9, v[84:87], s[92:93]
	ds_read_b32 v64, v7 offset:64
	ds_read_b32 v65, v7 offset:196
	ds_read_b32 v66, v7 offset:328
	ds_read_b32 v67, v7 offset:460
	ds_read_b32 v68, v7 offset:592
	ds_read_b32 v69, v7 offset:724
	ds_read_b32 v70, v7 offset:856
	ds_read_b32 v71, v7 offset:988
	s_waitcnt lgkmcnt(0)
	v_cvt_pk_bf16_f32 v88, v64, v65
	v_cvt_pk_bf16_f32 v89, v66, v67
	v_cvt_pk_bf16_f32 v90, v68, v69
	v_cvt_pk_bf16_f32 v91, v70, v71
	global_store_dwordx4 v10, v[88:91], s[92:93]
	ds_read_b32 v72, v7 offset:96
	ds_read_b32 v73, v7 offset:228
	ds_read_b32 v74, v7 offset:360
	ds_read_b32 v75, v7 offset:492
	ds_read_b32 v76, v7 offset:624
	ds_read_b32 v77, v7 offset:756
	ds_read_b32 v78, v7 offset:888
	ds_read_b32 v79, v7 offset:1020
	s_waitcnt lgkmcnt(0)
	v_cvt_pk_bf16_f32 v92, v72, v73
	v_cvt_pk_bf16_f32 v93, v74, v75
	v_cvt_pk_bf16_f32 v94, v76, v77
	v_cvt_pk_bf16_f32 v95, v78, v79
	global_store_dwordx4 v11, v[92:95], s[92:93]
	s_add_i32 s85, s85, 0x600
	s_branch .Lgconv_loop
.Lgconv_done:
	s_mov_b64 s[0:1], 0
.LBB0_897:
	s_and_b64 vcc, exec, s[0:1]
	s_cbranch_vccz .LBB0_967
	s_mov_b32 s0, 0
	s_lshl_b32 s38, s2, 5
	v_mbcnt_lo_u32_b32 v0, -1, s0
	v_mbcnt_hi_u32_b32 v0, -1, v0
	v_or_b32_e32 v0, s24, v0
	s_mul_i32 s0, s2, 0x1d8000
	v_readfirstlane_b32 s40, v0
	s_ashr_i32 s41, s40, 6
	v_and_b32_e32 v1, 15, v0
	s_lshl_b32 s50, s41, 4
	v_or_b32_e32 v72, s50, v1
	v_ashrrev_i32_e32 v73, 31, v72
	v_lshl_add_u64 v[2:3], v[72:73], 2, s[80:81]
	global_load_dword v73, v[2:3], off
	v_and_b32_e32 v2, 63, v0
	s_mul_hi_i32 s1, s38, 0xec00
	s_add_u32 s0, s22, s0
	s_addc_u32 s1, s23, s1
	s_lshl_b32 s4, s41, 10
	v_lshlrev_b32_e32 v4, 4, v2
	v_mov_b32_e32 v5, 0
	v_lshl_add_u64 v[4:5], s[0:1], 0, v[4:5]
	s_mov_b64 s[0:1], 0x17d2a000
	s_cmp_lt_i32 s41, 59
	s_cselect_b64 s[6:7], -1, 0
	s_cmp_gt_i32 s41, 58
	v_lshl_add_u64 v[74:75], v[4:5], 0, s[0:1]
	s_cbranch_scc1 .LBB0_900
	s_ashr_i32 s5, s4, 31
	v_lshl_add_u64 v[4:5], v[74:75], 0, s[4:5]
	s_add_i32 m0, s4, 0
	s_nop 0
	global_load_lds_dwordx4 v[4:5], off
